# P0 load balance: w_uq/w_ukv conversion moved to workgroups 128+ (max 2 extra steps per WG), on top of v63
# baseline (speedup 1.0000x reference)
; __device__ __forceinline__ unsigned cvt_pk_bf16(float lo, float hi) { unsigned r; asm volatile("v_cvt_pk_bf16_f32 %0, %1, %2" : "=v"(r) : "v"(lo), "v"(hi)); return r; }
; __device__ __forceinline__ void transpose_w(const float* __restrict__ src0, const float* __restrict__ src1, int K, int N, bf16_t* __restrict__ dst, int P, int type, float* tl, int first, int stride) {
;   const int tid = threadIdx.x, nkt = K / 128, ntiles = nkt * (P / 64), c32 = tid & 31, kq = tid >> 5;
;   for (int t = first; t < ntiles; t += stride) {
;     const int pi = t / nkt, ki = t - pi * nkt, p0 = pi * 64, k0 = ki * 128;
;     int u0, u1; const int n0a = perm_n0(type, p0, u0), n0b = perm_n0(type, p0 + 32, u1);
;     const float* sa = (u0 ? src1 : src0) + (size_t)k0 * N + (n0a < 0 ? 0 : n0a) + c32; const float* sb = (u1 ? src1 : src0) + (size_t)k0 * N + (n0b < 0 ? 0 : n0b) + c32;
;     float va[8], vb[8];
; #pragma unroll
;     for (int i = 0; i < 8; ++i) { va[i] = sa[(size_t)(kq + 16 * i) * N]; vb[i] = sb[(size_t)(kq + 16 * i) * N]; }
;     __syncthreads();
; #pragma unroll
;     for (int i = 0; i < 8; ++i) { tl[(kq + 16 * i) * 33 + c32] = n0a < 0 ? 0.f : va[i]; tl[128 * 33 + (kq + 16 * i) * 33 + c32] = n0b < 0 ? 0.f : vb[i]; }
;     __syncthreads();
;     const int row = tid >> 4, kc = (tid & 15) * 8;
; #pragma unroll
;     for (int h = 0; h < 2; ++h) { const float* q = tl + h * 128 * 33 + kc * 33 + row;
;       u32x4 w; w.x = cvt_pk_bf16(q[0], q[33]); w.y = cvt_pk_bf16(q[66], q[99]); w.z = cvt_pk_bf16(q[132], q[165]); w.w = cvt_pk_bf16(q[198], q[231]);
;       *(u32x4*)(dst + (size_t)(p0 + h * 32 + row) * K + k0 + kc) = w; }
;   }
; }
; __global__ void __launch_bounds__(512, 2) fwd_megakernel(const Params p) {
;     ...
;     transpose_w(p.in[I_WUQ], nullptr, 512, 1536, (bf16_t*)(ws + O_WUQ), 1536, PM_UQ, tl, bid, G);
.LBB0_36:
	s_mov_b32 s98, s14
	s_cmpk_eq_i32 s78, 0x100
	s_cbranch_scc0 .Luq_noremap
	s_sub_u32 s98, s14, 0x80
.Luq_noremap:
	s_cmp_gt_u32 s98, 0x5f
	s_cbranch_scc1 .LBB0_47
	v_lshlrev_b32_e32 v2, 1, v32
	v_mov_b32_e32 v3, 0
	v_lshl_add_u64 v[4:5], s[74:75], 0, v[2:3]
	s_mov_b64 s[0:1], 0x1000000
	v_lshl_add_u64 v[4:5], v[4:5], 0, s[0:1]
	s_movk_i32 s0, 0x600
	v_mov_b32_e32 v1, 0x18000
	v_mad_u32_u24 v6, v33, s0, v1
	v_mov_b32_e32 v1, 0x1e000
	v_mad_u32_u24 v8, v33, s0, v1
	v_mov_b32_e32 v1, 0x24000
	v_mad_u32_u24 v10, v33, s0, v1
	v_mov_b32_e32 v1, 0x2a000
	v_mul_u32_u24_e32 v2, 0x600, v33
	v_mad_u32_u24 v12, v33, s0, v1
	s_mov_b32 s4, 0x18000
	s_lshl_b32 s5, s98, 7
	s_lshl_b32 s6, s78, 7
	s_mov_b32 s1, 0
	v_mov_b32_e32 v1, v3
	v_lshlrev_b32_e32 v2, 2, v2
	s_mov_b32 s7, 0x30000
	s_mov_b32 s15, 0x48000
	v_lshlrev_b32_e32 v6, 2, v6
	v_mov_b32_e32 v7, v3
	v_lshlrev_b32_e32 v8, 2, v8
	v_mov_b32_e32 v9, v3
	v_lshlrev_b32_e32 v10, 2, v10
	v_mov_b32_e32 v11, v3
	v_lshlrev_b32_e32 v12, 2, v12
	v_mov_b32_e32 v13, v3
	v_add_u32_e32 v14, 0x4000, v22
	v_add_u32_e32 v15, 0x4400, v22
	s_mov_b32 s33, s98
	s_branch .LBB0_39

; __device__ __forceinline__ unsigned cvt_pk_bf16(float lo, float hi) { unsigned r; asm volatile("v_cvt_pk_bf16_f32 %0, %1, %2" : "=v"(r) : "v"(lo), "v"(hi)); return r; }
; __device__ __forceinline__ void transpose_w(const float* __restrict__ src0, const float* __restrict__ src1, int K, int N, bf16_t* __restrict__ dst, int P, int type, float* tl, int first, int stride) {
;   const int tid = threadIdx.x, nkt = K / 128, ntiles = nkt * (P / 64), c32 = tid & 31, kq = tid >> 5;
;   for (int t = first; t < ntiles; t += stride) {
;     const int pi = t / nkt, ki = t - pi * nkt, p0 = pi * 64, k0 = ki * 128;
;     int u0, u1; const int n0a = perm_n0(type, p0, u0), n0b = perm_n0(type, p0 + 32, u1);
;     const float* sa = (u0 ? src1 : src0) + (size_t)k0 * N + (n0a < 0 ? 0 : n0a) + c32; const float* sb = (u1 ? src1 : src0) + (size_t)k0 * N + (n0b < 0 ? 0 : n0b) + c32;
;     float va[8], vb[8];
; #pragma unroll
;     for (int i = 0; i < 8; ++i) { va[i] = sa[(size_t)(kq + 16 * i) * N]; vb[i] = sb[(size_t)(kq + 16 * i) * N]; }
;     __syncthreads();
; #pragma unroll
;     for (int i = 0; i < 8; ++i) { tl[(kq + 16 * i) * 33 + c32] = n0a < 0 ? 0.f : va[i]; tl[128 * 33 + (kq + 16 * i) * 33 + c32] = n0b < 0 ? 0.f : vb[i]; }
;     __syncthreads();
;     const int row = tid >> 4, kc = (tid & 15) * 8;
; #pragma unroll
;     for (int h = 0; h < 2; ++h) { const float* q = tl + h * 128 * 33 + kc * 33 + row;
;       u32x4 w; w.x = cvt_pk_bf16(q[0], q[33]); w.y = cvt_pk_bf16(q[66], q[99]); w.z = cvt_pk_bf16(q[132], q[165]); w.w = cvt_pk_bf16(q[198], q[231]);
;       *(u32x4*)(dst + (size_t)(p0 + h * 32 + row) * K + k0 + kc) = w; }
;   }
; }
; __global__ void __launch_bounds__(512, 2) fwd_megakernel(const Params p) {
;     ...
;     transpose_w(p.in[I_WUKV], nullptr, 256, 2048, (bf16_t*)(ws + O_WUKV), 2048, PM_ID, tl, bid, G);
.LBB0_47:
	v_add_u32_e32 v20, 16, v33
	v_or_b32_e32 v21, 32, v33
	v_add_u32_e32 v42, 48, v33
	v_or_b32_e32 v43, 64, v33
	v_add_u32_e32 v44, 0x50, v33
	v_or_b32_e32 v50, 0x60, v33
	v_add_u32_e32 v51, 0x70, v33
	s_mov_b32 s99, s14
	s_cmpk_eq_i32 s78, 0x100
	s_cbranch_scc0 .Lukv_noremap
	s_sub_u32 s99, s14, 0xc0
.Lukv_noremap:
	s_cmp_gt_u32 s99, 63
	v_lshlrev_b32_e32 v41, 11, v33
	v_mov_b32_e32 v1, 0
	v_lshlrev_b32_e32 v40, 11, v20
	v_lshlrev_b32_e32 v39, 11, v21
	v_lshlrev_b32_e32 v38, 11, v42
	v_lshlrev_b32_e32 v37, 11, v43
	v_lshlrev_b32_e32 v36, 11, v44
	v_lshlrev_b32_e32 v35, 11, v50
	v_lshlrev_b32_e32 v34, 11, v51
	s_cbranch_scc1 .LBB0_50
	v_lshlrev_b32_e32 v2, 1, v32
	v_mov_b32_e32 v3, v1
	v_lshl_add_u64 v[2:3], s[74:75], 0, v[2:3]
	s_mov_b64 s[0:1], 0x1180000
	v_lshl_add_u64 v[2:3], v[2:3], 0, s[0:1]
	s_lshl_b32 s4, s99, 7
	s_lshl_b32 s5, s78, 7
	s_mov_b32 s1, 0
	v_lshlrev_b32_e32 v4, 2, v41
	v_mov_b32_e32 v5, v1
	v_lshlrev_b32_e32 v6, 2, v40
	v_mov_b32_e32 v7, v1
	v_lshlrev_b32_e32 v8, 2, v39
	v_mov_b32_e32 v9, v1
	v_lshlrev_b32_e32 v10, 2, v38
	v_mov_b32_e32 v11, v1
	v_lshlrev_b32_e32 v12, 2, v37
	v_mov_b32_e32 v13, v1
	v_lshlrev_b32_e32 v14, 2, v36
	v_mov_b32_e32 v15, v1
	v_lshlrev_b32_e32 v16, 2, v35
	v_mov_b32_e32 v17, v1
	v_lshlrev_b32_e32 v18, 2, v34
	v_mov_b32_e32 v19, v1
	v_add_u32_e32 v45, 0x4000, v22
	v_add_u32_e32 v46, 0x4400, v22
	s_mov_b32 s6, s99
